# NA attention: static s_setprio 1 for waves 4-7 too (plus MLA prio and write-through 16-byte stores)
# baseline (speedup 1.0000x reference)
; #define SBAR() __builtin_amdgcn_sched_barrier(0)
; __device__ __forceinline__ int crow(int r, int hi) { return (r & 3) + 8 * (r >> 2) + 4 * hi; }
; __device__ __forceinline__ void na_unit3(char* lds, const bf16_t* __restrict__ Qp, const bf16_t* __restrict__ Knp, const bf16_t* __restrict__ Vp, ...
;     ...
;   if (hi == 0) li_l[r32] = l_reg; asm volatile("s_waitcnt lgkmcnt(0)" ::: "memory");
;   float rli[16];
; #pragma unroll
;   for (int r = 0; r < 16; ++r) rli[r] = __builtin_amdgcn_rcpf(li_l[crow(r, hi)]);
;   { unsigned zr[16][4];
; #pragma unroll
;     for (int r = 0; r < 16; ++r) { const long trow = wid * QBLK + crow(r, hi);
; #pragma unroll
;       for (int d0 = 0; d0 < 4; ++d0) zr[r][d0] = Zp[trow * LDZ + d0 * 32 + r32]; }
;     asm volatile("s_waitcnt vmcnt(0)" ::: "memory"); SBAR();
.LBB0_275:
	s_or_b64 exec, exec, s[6:7]
	s_waitcnt lgkmcnt(0)
	v_lshl_add_u32 v1, v222, 4, s26
	ds_read_b128 v[2:5], v1
	ds_read_b128 v[6:9], v1 offset:32
	s_lshl_b64 s[0:1], s[82:83], 1
	s_add_u32 s6, s81, s0
	s_addc_u32 s7, s84, s1
	s_waitcnt lgkmcnt(1)
	v_rcp_f32_e32 v171, v2
	v_rcp_f32_e32 v166, v3
	v_rcp_f32_e32 v161, v4
	v_rcp_f32_e32 v155, v5
	ds_read_b128 v[2:5], v1 offset:64
	s_lshl_b32 s0, s77, 15
	s_add_u32 s0, s34, s0
	s_addc_u32 s1, s35, 0
	s_lshl_b64 s[0:1], s[0:1], 7
	s_waitcnt lgkmcnt(0)
	v_rcp_f32_e32 v128, v2
	v_rcp_f32_e32 v122, v3
	v_rcp_f32_e32 v117, v4
	v_rcp_f32_e32 v111, v5
	ds_read_b128 v[2:5], v1 offset:96
	s_add_u32 s34, s28, s0
	v_lshl_or_b32 v98, v222, 2, s80
	s_addc_u32 s35, s29, s1
	s_mov_b64 s[0:1], 0xc000000
	s_waitcnt lgkmcnt(0)
	v_rcp_f32_e32 v105, v2
	v_rcp_f32_e32 v103, v3
	v_lshlrev_b32_e32 v2, 1, v221
	v_mov_b32_e32 v3, v0
	v_rcp_f32_e32 v102, v4
	v_rcp_f32_e32 v1, v5
	v_lshl_add_u64 v[4:5], s[6:7], 0, v[2:3]
	v_ashrrev_i32_e32 v99, 31, v98
	v_lshl_add_u64 v[100:101], v[4:5], 0, s[0:1]
	v_lshlrev_b64 v[4:5], 9, v[98:99]
	v_or_b32_e32 v96, 1, v98
	v_lshl_add_u64 v[4:5], v[100:101], 0, v[4:5]
	v_ashrrev_i32_e32 v97, 31, v96
	global_load_ushort v180, v[4:5], off
	global_load_ushort v177, v[4:5], off offset:64
	global_load_ushort v176, v[4:5], off offset:128
	global_load_ushort v175, v[4:5], off offset:192
	v_lshlrev_b64 v[4:5], 9, v[96:97]
	v_or_b32_e32 v94, 2, v98
	v_lshl_add_u64 v[4:5], v[100:101], 0, v[4:5]
	v_ashrrev_i32_e32 v95, 31, v94
	global_load_ushort v174, v[4:5], off
	global_load_ushort v173, v[4:5], off offset:64
	global_load_ushort v172, v[4:5], off offset:128
	global_load_ushort v170, v[4:5], off offset:192
	v_lshlrev_b64 v[4:5], 9, v[94:95]
	v_or_b32_e32 v92, 3, v98
	v_lshl_add_u64 v[4:5], v[100:101], 0, v[4:5]
	v_ashrrev_i32_e32 v93, 31, v92
	global_load_ushort v169, v[4:5], off
	global_load_ushort v168, v[4:5], off offset:64
	global_load_ushort v167, v[4:5], off offset:128
	global_load_ushort v165, v[4:5], off offset:192
	v_lshlrev_b64 v[4:5], 9, v[92:93]
	v_or_b32_e32 v90, 8, v98
	v_lshl_add_u64 v[4:5], v[100:101], 0, v[4:5]
	v_ashrrev_i32_e32 v91, 31, v90
	global_load_ushort v164, v[4:5], off
	global_load_ushort v163, v[4:5], off offset:64
	global_load_ushort v162, v[4:5], off offset:128
	global_load_ushort v160, v[4:5], off offset:192
	v_lshlrev_b64 v[4:5], 9, v[90:91]
	v_or_b32_e32 v88, 9, v98
	v_lshl_add_u64 v[4:5], v[100:101], 0, v[4:5]
	v_ashrrev_i32_e32 v89, 31, v88
	global_load_ushort v159, v[4:5], off
	global_load_ushort v158, v[4:5], off offset:64
	global_load_ushort v157, v[4:5], off offset:128
	global_load_ushort v156, v[4:5], off offset:192
	v_lshlrev_b64 v[4:5], 9, v[88:89]
	v_or_b32_e32 v86, 10, v98
	v_lshl_add_u64 v[4:5], v[100:101], 0, v[4:5]
	v_ashrrev_i32_e32 v87, 31, v86
	global_load_ushort v154, v[4:5], off
	global_load_ushort v153, v[4:5], off offset:64
	global_load_ushort v152, v[4:5], off offset:128
	global_load_ushort v151, v[4:5], off offset:192
	v_lshlrev_b64 v[4:5], 9, v[86:87]
	v_or_b32_e32 v84, 11, v98
	v_lshl_add_u64 v[4:5], v[100:101], 0, v[4:5]
	v_ashrrev_i32_e32 v85, 31, v84
	global_load_ushort v150, v[4:5], off
	global_load_ushort v148, v[4:5], off offset:64
	global_load_ushort v147, v[4:5], off offset:128
	global_load_ushort v146, v[4:5], off offset:192
	v_lshlrev_b64 v[4:5], 9, v[84:85]
	v_or_b32_e32 v82, 16, v98
	v_lshl_add_u64 v[4:5], v[100:101], 0, v[4:5]
	v_ashrrev_i32_e32 v83, 31, v82
	global_load_ushort v145, v[4:5], off
	global_load_ushort v143, v[4:5], off offset:64
	global_load_ushort v142, v[4:5], off offset:128
	global_load_ushort v141, v[4:5], off offset:192
	v_lshlrev_b64 v[4:5], 9, v[82:83]
	v_or_b32_e32 v80, 17, v98
	v_lshl_add_u64 v[4:5], v[100:101], 0, v[4:5]
	v_ashrrev_i32_e32 v81, 31, v80
	global_load_ushort v140, v[4:5], off
	global_load_ushort v138, v[4:5], off offset:64
	global_load_ushort v137, v[4:5], off offset:128
	global_load_ushort v136, v[4:5], off offset:192
	v_lshlrev_b64 v[4:5], 9, v[80:81]
	v_or_b32_e32 v14, 18, v98
	v_lshl_add_u64 v[4:5], v[100:101], 0, v[4:5]
	v_ashrrev_i32_e32 v15, 31, v14
	global_load_ushort v135, v[4:5], off
	global_load_ushort v134, v[4:5], off offset:64
	global_load_ushort v132, v[4:5], off offset:128
	global_load_ushort v131, v[4:5], off offset:192
	v_lshlrev_b64 v[4:5], 9, v[14:15]
	v_or_b32_e32 v12, 19, v98
	v_lshl_add_u64 v[4:5], v[100:101], 0, v[4:5]
	v_ashrrev_i32_e32 v13, 31, v12
	global_load_ushort v130, v[4:5], off
	global_load_ushort v129, v[4:5], off offset:64
	global_load_ushort v127, v[4:5], off offset:128
	global_load_ushort v126, v[4:5], off offset:192
	v_lshlrev_b64 v[4:5], 9, v[12:13]
	v_or_b32_e32 v10, 24, v98
	v_lshl_add_u64 v[4:5], v[100:101], 0, v[4:5]
	v_ashrrev_i32_e32 v11, 31, v10
	v_rcp_f32_e32 v139, v8
	global_load_ushort v125, v[4:5], off
	global_load_ushort v124, v[4:5], off offset:64
	global_load_ushort v123, v[4:5], off offset:128
	global_load_ushort v121, v[4:5], off offset:192
	v_lshlrev_b64 v[4:5], 9, v[10:11]
	v_or_b32_e32 v8, 25, v98
	v_rcp_f32_e32 v133, v9
	v_lshl_add_u64 v[4:5], v[100:101], 0, v[4:5]
	v_ashrrev_i32_e32 v9, 31, v8
	v_rcp_f32_e32 v149, v6
	global_load_ushort v120, v[4:5], off
	global_load_ushort v119, v[4:5], off offset:64
	global_load_ushort v118, v[4:5], off offset:128
	global_load_ushort v116, v[4:5], off offset:192
	v_lshlrev_b64 v[4:5], 9, v[8:9]
	v_or_b32_e32 v6, 26, v98
	v_rcp_f32_e32 v144, v7
	v_lshl_add_u64 v[4:5], v[100:101], 0, v[4:5]
	v_ashrrev_i32_e32 v7, 31, v6
	global_load_ushort v115, v[4:5], off
	global_load_ushort v114, v[4:5], off offset:64
	global_load_ushort v113, v[4:5], off offset:128
	global_load_ushort v112, v[4:5], off offset:192
	v_lshlrev_b64 v[4:5], 9, v[6:7]
	v_lshl_add_u64 v[4:5], v[100:101], 0, v[4:5]
	global_load_ushort v110, v[4:5], off
	global_load_ushort v109, v[4:5], off offset:64
	global_load_ushort v108, v[4:5], off offset:128
	global_load_ushort v107, v[4:5], off offset:192
	v_or_b32_e32 v4, 27, v98
	v_ashrrev_i32_e32 v5, 31, v4
	v_lshlrev_b64 v[178:179], 9, v[4:5]
	v_lshl_add_u64 v[178:179], v[100:101], 0, v[178:179]
	global_load_ushort v106, v[178:179], off
	global_load_ushort v104, v[178:179], off offset:64
	global_load_ushort v101, v[178:179], off offset:128
	global_load_ushort v100, v[178:179], off offset:192
	s_waitcnt vmcnt(0)
; __device__ __forceinline__ float bf2f(unsigned h) { return __uint_as_float(h << 16); }
; __device__ __forceinline__ unsigned f2bf(float f) { unsigned u = __float_as_uint(f); return (u + 0x7fffu + ((u >> 16) & 1u)) >> 16; }
; __device__ __forceinline__ int crow(int r, int hi) { return (r & 3) + 8 * (r >> 2) + 4 * hi; }
; __device__ __forceinline__ void na_unit3(char* lds, const bf16_t* __restrict__ Qp, const bf16_t* __restrict__ Knp, const bf16_t* __restrict__ Vp, ...
;     ...
;     for (int r = 0; r < 16; ++r) { const long trow = wid * QBLK + crow(r, hi);
; #pragma unroll
;       for (int d0 = 0; d0 < 4; ++d0) { const float z = bf2f(zr[r][d0]); const float v = o[d0][r] * rli[r];
;         const float g = v * z * __builtin_amdgcn_rcpf(1.f + __expf(-z));
;         Op[((size_t)(d0 >> 1) * M_TOK + trow) * 64 + (d0 & 1) * 32 + r32] = (bf16_t)f2bf(g); } } }
; __global__ void __launch_bounds__(NWAVES * 64, 2) fwd_mega(Args args) {
;     ...
;             for (int rep = 0; rep < REP_NA; ++rep) for (int u = vcu; u < 1024; u += G) {
	s_waitcnt vmcnt(62)
	v_lshlrev_b32_e32 v178, 16, v180
	v_mul_f32_e32 v64, v64, v171
	v_mul_f32_e32 v64, v64, v178
	v_mul_f32_e32 v178, 0xbfb8aa3b, v178
	v_exp_f32_e32 v178, v178
	v_lshlrev_b64 v[98:99], 7, v[98:99]
	v_lshl_add_u64 v[98:99], s[34:35], 0, v[98:99]
	v_lshl_add_u64 v[98:99], v[98:99], 0, v[2:3]
	v_add_f32_e32 v178, 1.0, v178
	v_rcp_f32_e32 v178, v178
	v_mul_f32_e32 v48, v48, v171
	v_mul_f32_e32 v32, v32, v171
	v_mul_f32_e32 v16, v16, v171
	v_mul_f32_e32 v64, v64, v178
	v_bfe_u32 v178, v64, 16, 1
	v_add3_u32 v64, v64, v178, s63
	global_store_short_d16_hi v[98:99], v64, off
	v_lshlrev_b32_e32 v64, 16, v177
	v_mul_f32_e32 v48, v48, v64
	v_mul_f32_e32 v64, 0xbfb8aa3b, v64
	v_exp_f32_e32 v64, v64
	v_mul_f32_e32 v17, v17, v166
	v_mul_f32_e32 v18, v18, v161
	v_mul_f32_e32 v19, v19, v155
	v_add_f32_e32 v64, 1.0, v64
	v_rcp_f32_e32 v64, v64
	v_lshlrev_b64 v[14:15], 7, v[14:15]
	v_lshl_add_u64 v[14:15], s[34:35], 0, v[14:15]
	v_lshl_add_u64 v[14:15], v[14:15], 0, v[2:3]
	v_mul_f32_e32 v48, v48, v64
	v_bfe_u32 v64, v48, 16, 1
	v_add3_u32 v48, v48, v64, s63
	global_store_short_d16_hi v[98:99], v48, off offset:64
	s_waitcnt vmcnt(62)
	v_lshlrev_b32_e32 v48, 16, v176
	v_mul_f32_e32 v32, v32, v48
	v_mul_f32_e32 v48, 0xbfb8aa3b, v48
	v_exp_f32_e32 v48, v48
	v_add_co_u32_e32 v98, vcc, s93, v98
	v_lshlrev_b64 v[12:13], 7, v[12:13]
	v_add_f32_e32 v48, 1.0, v48
	v_rcp_f32_e32 v48, v48
	v_addc_co_u32_e32 v99, vcc, 0, v99, vcc
	v_lshl_add_u64 v[12:13], s[34:35], 0, v[12:13]
	v_mul_f32_e32 v32, v32, v48
	v_bfe_u32 v48, v32, 16, 1
	v_add3_u32 v32, v32, v48, s63
	global_store_short_d16_hi v[98:99], v32, off
	v_lshlrev_b32_e32 v32, 16, v175
	v_mul_f32_e32 v16, v16, v32
	v_mul_f32_e32 v32, 0xbfb8aa3b, v32
	v_exp_f32_e32 v32, v32
	v_lshl_add_u64 v[12:13], v[12:13], 0, v[2:3]
	v_lshlrev_b64 v[10:11], 7, v[10:11]
	v_lshl_add_u64 v[10:11], s[34:35], 0, v[10:11]
	v_add_f32_e32 v32, 1.0, v32
	v_rcp_f32_e32 v32, v32
	v_lshl_add_u64 v[10:11], v[10:11], 0, v[2:3]
	v_lshlrev_b64 v[8:9], 7, v[8:9]
	v_lshl_add_u64 v[8:9], s[34:35], 0, v[8:9]
	v_mul_f32_e32 v16, v16, v32
	v_bfe_u32 v32, v16, 16, 1
	v_add3_u32 v16, v16, v32, s63
	global_store_short_d16_hi v[98:99], v16, off offset:64
	s_waitcnt vmcnt(62)
	v_lshlrev_b32_e32 v16, 16, v174
	v_mul_f32_e32 v32, v65, v166
	v_mul_f32_e32 v32, v32, v16
	v_mul_f32_e32 v16, 0xbfb8aa3b, v16
	v_exp_f32_e32 v16, v16
	v_lshlrev_b64 v[64:65], 7, v[96:97]
	v_lshl_add_u64 v[64:65], s[34:35], 0, v[64:65]
	v_lshl_add_u64 v[64:65], v[64:65], 0, v[2:3]
	v_add_f32_e32 v16, 1.0, v16
	v_rcp_f32_e32 v16, v16
	v_lshl_add_u64 v[8:9], v[8:9], 0, v[2:3]
	v_lshlrev_b64 v[6:7], 7, v[6:7]
	v_lshl_add_u64 v[6:7], s[34:35], 0, v[6:7]
	v_mul_f32_e32 v16, v32, v16
	v_bfe_u32 v32, v16, 16, 1
	v_add3_u32 v16, v16, v32, s63
	global_store_short_d16_hi v[64:65], v16, off
	v_lshlrev_b32_e32 v16, 16, v173
	v_mul_f32_e32 v32, v49, v166
	v_mul_f32_e32 v32, v32, v16
	v_mul_f32_e32 v16, 0xbfb8aa3b, v16
	v_exp_f32_e32 v16, v16
	v_lshl_add_u64 v[6:7], v[6:7], 0, v[2:3]
	v_lshlrev_b64 v[4:5], 7, v[4:5]
	v_lshl_add_u64 v[4:5], s[34:35], 0, v[4:5]
	v_add_f32_e32 v16, 1.0, v16
	v_rcp_f32_e32 v16, v16
	v_readlane_b32 s0, v254, 14
	s_add_i32 s76, s76, s66
	s_add_i32 s75, s75, s0
	v_mul_f32_e32 v16, v32, v16
	v_bfe_u32 v32, v16, 16, 1
	v_add3_u32 v16, v16, v32, s63
	global_store_short_d16_hi v[64:65], v16, off offset:64
	s_waitcnt vmcnt(62)
	v_lshlrev_b32_e32 v16, 16, v172
	v_mul_f32_e32 v32, v33, v166
	v_mul_f32_e32 v32, v32, v16
	v_mul_f32_e32 v16, 0xbfb8aa3b, v16
	v_exp_f32_e32 v16, v16
	s_cmpk_gt_i32 s76, 0x3ff
	v_add_f32_e32 v16, 1.0, v16
	v_rcp_f32_e32 v16, v16
	s_nop 0
	v_mul_f32_e32 v16, v32, v16
	v_bfe_u32 v32, v16, 16, 1
	v_add3_u32 v16, v16, v32, s63
	v_add_co_u32_e32 v32, vcc, s93, v64
	s_nop 1
	v_addc_co_u32_e32 v33, vcc, 0, v65, vcc
	global_store_short_d16_hi v[32:33], v16, off
	v_lshlrev_b32_e32 v16, 16, v170
	v_mul_f32_e32 v17, v17, v16
	v_mul_f32_e32 v16, 0xbfb8aa3b, v16
	v_exp_f32_e32 v16, v16
	s_nop 0
	v_add_f32_e32 v16, 1.0, v16
	v_rcp_f32_e32 v16, v16
	s_nop 0
	v_mul_f32_e32 v16, v17, v16
	v_bfe_u32 v17, v16, 16, 1
	v_add3_u32 v16, v16, v17, s63
	global_store_short_d16_hi v[32:33], v16, off offset:64
	s_waitcnt vmcnt(62)
	v_lshlrev_b32_e32 v16, 16, v169
	v_mul_f32_e32 v17, v66, v161
	v_mul_f32_e32 v17, v17, v16
	v_mul_f32_e32 v16, 0xbfb8aa3b, v16
	v_exp_f32_e32 v16, v16
	v_mul_f32_e32 v33, v50, v161
	v_add_f32_e32 v16, 1.0, v16
	v_rcp_f32_e32 v16, v16
	s_nop 0
	v_mul_f32_e32 v16, v17, v16
	v_bfe_u32 v17, v16, 16, 1
	v_add3_u32 v32, v16, v17, s63
	v_lshlrev_b64 v[16:17], 7, v[94:95]
	v_lshl_add_u64 v[16:17], s[34:35], 0, v[16:17]
	v_lshl_add_u64 v[16:17], v[16:17], 0, v[2:3]
	global_store_short_d16_hi v[16:17], v32, off
	v_lshlrev_b32_e32 v32, 16, v168
	v_mul_f32_e32 v33, v33, v32
	v_mul_f32_e32 v32, 0xbfb8aa3b, v32
	v_exp_f32_e32 v32, v32
	s_nop 0
	v_add_f32_e32 v32, 1.0, v32
	v_rcp_f32_e32 v32, v32
	s_nop 0
	v_mul_f32_e32 v32, v33, v32
	v_bfe_u32 v33, v32, 16, 1
	v_add3_u32 v32, v32, v33, s63
	global_store_short_d16_hi v[16:17], v32, off offset:64
	s_waitcnt vmcnt(62)
	v_lshlrev_b32_e32 v32, 16, v167
	v_mul_f32_e32 v33, v34, v161
	v_mul_f32_e32 v33, v33, v32
	v_mul_f32_e32 v32, 0xbfb8aa3b, v32
	v_exp_f32_e32 v32, v32
	v_add_co_u32_e32 v16, vcc, s93, v16
	v_add_f32_e32 v32, 1.0, v32
	v_rcp_f32_e32 v32, v32
	v_addc_co_u32_e32 v17, vcc, 0, v17, vcc
	v_mul_f32_e32 v32, v33, v32
	v_bfe_u32 v33, v32, 16, 1
	v_add3_u32 v32, v32, v33, s63
	global_store_short_d16_hi v[16:17], v32, off
	v_lshlrev_b32_e32 v32, 16, v165
	v_mul_f32_e32 v18, v18, v32
	v_mul_f32_e32 v32, 0xbfb8aa3b, v32
	v_exp_f32_e32 v32, v32
	s_nop 0
	v_add_f32_e32 v32, 1.0, v32
	v_rcp_f32_e32 v32, v32
	s_nop 0
	v_mul_f32_e32 v18, v18, v32
	v_bfe_u32 v32, v18, 16, 1
	v_add3_u32 v18, v18, v32, s63
	global_store_short_d16_hi v[16:17], v18, off offset:64
	s_waitcnt vmcnt(62)
; __device__ __forceinline__ float bf2f(unsigned h) { return __uint_as_float(h << 16); }
; __device__ __forceinline__ unsigned f2bf(float f) { unsigned u = __float_as_uint(f); return (u + 0x7fffu + ((u >> 16) & 1u)) >> 16; }
; __device__ __forceinline__ int crow(int r, int hi) { return (r & 3) + 8 * (r >> 2) + 4 * hi; }
; __device__ __forceinline__ void na_unit3(char* lds, const bf16_t* __restrict__ Qp, const bf16_t* __restrict__ Knp, const bf16_t* __restrict__ Vp, ...
;     ...
;     for (int r = 0; r < 16; ++r) { const long trow = wid * QBLK + crow(r, hi);
; #pragma unroll
;       for (int d0 = 0; d0 < 4; ++d0) { const float z = bf2f(zr[r][d0]); const float v = o[d0][r] * rli[r];
;         const float g = v * z * __builtin_amdgcn_rcpf(1.f + __expf(-z));
;         Op[((size_t)(d0 >> 1) * M_TOK + trow) * 64 + (d0 & 1) * 32 + r32] = (bf16_t)f2bf(g); } } }
	v_lshlrev_b32_e32 v16, 16, v164
	v_mul_f32_e32 v17, v67, v155
	v_mul_f32_e32 v17, v17, v16
	v_mul_f32_e32 v16, 0xbfb8aa3b, v16
	v_exp_f32_e32 v16, v16
	v_mul_f32_e32 v32, v51, v155
	v_add_f32_e32 v16, 1.0, v16
	v_rcp_f32_e32 v16, v16
	s_nop 0
	v_mul_f32_e32 v16, v17, v16
	v_bfe_u32 v17, v16, 16, 1
	v_add3_u32 v18, v16, v17, s63
	v_lshlrev_b64 v[16:17], 7, v[92:93]
	v_lshl_add_u64 v[16:17], s[34:35], 0, v[16:17]
	v_lshl_add_u64 v[16:17], v[16:17], 0, v[2:3]
	global_store_short_d16_hi v[16:17], v18, off
	v_lshlrev_b32_e32 v18, 16, v163
	v_mul_f32_e32 v32, v32, v18
	v_mul_f32_e32 v18, 0xbfb8aa3b, v18
	v_exp_f32_e32 v18, v18
	s_nop 0
	v_add_f32_e32 v18, 1.0, v18
	v_rcp_f32_e32 v18, v18
	s_nop 0
	v_mul_f32_e32 v18, v32, v18
	v_bfe_u32 v32, v18, 16, 1
	v_add3_u32 v18, v18, v32, s63
	global_store_short_d16_hi v[16:17], v18, off offset:64
	s_waitcnt vmcnt(62)
	v_lshlrev_b32_e32 v18, 16, v162
	v_mul_f32_e32 v32, v35, v155
	v_mul_f32_e32 v32, v32, v18
	v_mul_f32_e32 v18, 0xbfb8aa3b, v18
	v_exp_f32_e32 v18, v18
	v_add_co_u32_e32 v16, vcc, s93, v16
	v_add_f32_e32 v18, 1.0, v18
	v_rcp_f32_e32 v18, v18
	v_addc_co_u32_e32 v17, vcc, 0, v17, vcc
	v_mul_f32_e32 v18, v32, v18
	v_bfe_u32 v32, v18, 16, 1
	v_add3_u32 v18, v18, v32, s63
	global_store_short_d16_hi v[16:17], v18, off
	v_lshlrev_b32_e32 v18, 16, v160
	v_mul_f32_e32 v19, v19, v18
	v_mul_f32_e32 v18, 0xbfb8aa3b, v18
	v_exp_f32_e32 v18, v18
	s_nop 0
	v_add_f32_e32 v18, 1.0, v18
	v_rcp_f32_e32 v18, v18
	s_nop 0
	v_mul_f32_e32 v18, v19, v18
	v_bfe_u32 v19, v18, 16, 1
	v_add3_u32 v18, v18, v19, s63
	global_store_short_d16_hi v[16:17], v18, off offset:64
	s_waitcnt vmcnt(62)
	v_lshlrev_b32_e32 v16, 16, v159
	v_mul_f32_e32 v17, v68, v149
	v_mul_f32_e32 v17, v17, v16
	v_mul_f32_e32 v16, 0xbfb8aa3b, v16
	v_exp_f32_e32 v16, v16
	v_mul_f32_e32 v19, v52, v149
	v_add_f32_e32 v16, 1.0, v16
	v_rcp_f32_e32 v16, v16
	s_nop 0
	v_mul_f32_e32 v16, v17, v16
	v_bfe_u32 v17, v16, 16, 1
	v_add3_u32 v18, v16, v17, s63
	v_lshlrev_b64 v[16:17], 7, v[90:91]
	v_lshl_add_u64 v[16:17], s[34:35], 0, v[16:17]
	v_lshl_add_u64 v[16:17], v[16:17], 0, v[2:3]
	global_store_short_d16_hi v[16:17], v18, off
	v_lshlrev_b32_e32 v18, 16, v158
	v_mul_f32_e32 v19, v19, v18
	v_mul_f32_e32 v18, 0xbfb8aa3b, v18
	v_exp_f32_e32 v18, v18
	s_nop 0
	v_add_f32_e32 v18, 1.0, v18
	v_rcp_f32_e32 v18, v18
	s_nop 0
	v_mul_f32_e32 v18, v19, v18
	v_bfe_u32 v19, v18, 16, 1
	v_add3_u32 v18, v18, v19, s63
	global_store_short_d16_hi v[16:17], v18, off offset:64
	s_waitcnt vmcnt(62)
	v_lshlrev_b32_e32 v18, 16, v157
	v_mul_f32_e32 v19, v36, v149
	v_mul_f32_e32 v19, v19, v18
	v_mul_f32_e32 v18, 0xbfb8aa3b, v18
	v_exp_f32_e32 v18, v18
	v_add_co_u32_e32 v16, vcc, s93, v16
	v_add_f32_e32 v18, 1.0, v18
	v_rcp_f32_e32 v18, v18
	v_addc_co_u32_e32 v17, vcc, 0, v17, vcc
	v_mul_f32_e32 v18, v19, v18
	v_bfe_u32 v19, v18, 16, 1
	v_add3_u32 v18, v18, v19, s63
	global_store_short_d16_hi v[16:17], v18, off
	v_lshlrev_b32_e32 v18, 16, v156
	v_mul_f32_e32 v19, v20, v149
	v_mul_f32_e32 v19, v19, v18
	v_mul_f32_e32 v18, 0xbfb8aa3b, v18
	v_exp_f32_e32 v18, v18
	s_nop 0
	v_add_f32_e32 v18, 1.0, v18
	v_rcp_f32_e32 v18, v18
	s_nop 0
	v_mul_f32_e32 v18, v19, v18
	v_bfe_u32 v19, v18, 16, 1
	v_add3_u32 v18, v18, v19, s63
	global_store_short_d16_hi v[16:17], v18, off offset:64
	s_waitcnt vmcnt(62)
	v_lshlrev_b32_e32 v16, 16, v154
	v_mul_f32_e32 v17, v69, v144
	v_mul_f32_e32 v17, v17, v16
	v_mul_f32_e32 v16, 0xbfb8aa3b, v16
	v_exp_f32_e32 v16, v16
	v_mul_f32_e32 v19, v53, v144
	v_add_f32_e32 v16, 1.0, v16
	v_rcp_f32_e32 v16, v16
	s_nop 0
	v_mul_f32_e32 v16, v17, v16
	v_bfe_u32 v17, v16, 16, 1
	v_add3_u32 v18, v16, v17, s63
	v_lshlrev_b64 v[16:17], 7, v[88:89]
	v_lshl_add_u64 v[16:17], s[34:35], 0, v[16:17]
	v_lshl_add_u64 v[16:17], v[16:17], 0, v[2:3]
	global_store_short_d16_hi v[16:17], v18, off
	v_lshlrev_b32_e32 v18, 16, v153
	v_mul_f32_e32 v19, v19, v18
	v_mul_f32_e32 v18, 0xbfb8aa3b, v18
	v_exp_f32_e32 v18, v18
	s_nop 0
	v_add_f32_e32 v18, 1.0, v18
	v_rcp_f32_e32 v18, v18
	s_nop 0
	v_mul_f32_e32 v18, v19, v18
	v_bfe_u32 v19, v18, 16, 1
	v_add3_u32 v18, v18, v19, s63
	global_store_short_d16_hi v[16:17], v18, off offset:64
	s_waitcnt vmcnt(62)
	v_lshlrev_b32_e32 v18, 16, v152
	v_mul_f32_e32 v19, v37, v144
	v_mul_f32_e32 v19, v19, v18
	v_mul_f32_e32 v18, 0xbfb8aa3b, v18
	v_exp_f32_e32 v18, v18
	v_add_co_u32_e32 v16, vcc, s93, v16
	v_add_f32_e32 v18, 1.0, v18
	v_rcp_f32_e32 v18, v18
	v_addc_co_u32_e32 v17, vcc, 0, v17, vcc
	v_mul_f32_e32 v18, v19, v18
	v_bfe_u32 v19, v18, 16, 1
	v_add3_u32 v18, v18, v19, s63
	global_store_short_d16_hi v[16:17], v18, off
	v_lshlrev_b32_e32 v18, 16, v151
	v_mul_f32_e32 v19, v21, v144
	v_mul_f32_e32 v19, v19, v18
	v_mul_f32_e32 v18, 0xbfb8aa3b, v18
	v_exp_f32_e32 v18, v18
	s_nop 0
	v_add_f32_e32 v18, 1.0, v18
	v_rcp_f32_e32 v18, v18
	s_nop 0
	v_mul_f32_e32 v18, v19, v18
	v_bfe_u32 v19, v18, 16, 1
	v_add3_u32 v18, v18, v19, s63
	global_store_short_d16_hi v[16:17], v18, off offset:64
	s_waitcnt vmcnt(62)
	v_lshlrev_b32_e32 v16, 16, v150
	v_mul_f32_e32 v17, v70, v139
	v_mul_f32_e32 v17, v17, v16
	v_mul_f32_e32 v16, 0xbfb8aa3b, v16
	v_exp_f32_e32 v16, v16
	v_mul_f32_e32 v19, v54, v139
	v_add_f32_e32 v16, 1.0, v16
	v_rcp_f32_e32 v16, v16
	s_nop 0
	v_mul_f32_e32 v16, v17, v16
	v_bfe_u32 v17, v16, 16, 1
	v_add3_u32 v18, v16, v17, s63
	v_lshlrev_b64 v[16:17], 7, v[86:87]
	v_lshl_add_u64 v[16:17], s[34:35], 0, v[16:17]
	v_lshl_add_u64 v[16:17], v[16:17], 0, v[2:3]
	global_store_short_d16_hi v[16:17], v18, off
	v_lshlrev_b32_e32 v18, 16, v148
	v_mul_f32_e32 v19, v19, v18
	v_mul_f32_e32 v18, 0xbfb8aa3b, v18
	v_exp_f32_e32 v18, v18
	s_nop 0
	v_add_f32_e32 v18, 1.0, v18
	v_rcp_f32_e32 v18, v18
	s_nop 0
	v_mul_f32_e32 v18, v19, v18
	v_bfe_u32 v19, v18, 16, 1
	v_add3_u32 v18, v18, v19, s63
	global_store_short_d16_hi v[16:17], v18, off offset:64
	s_waitcnt vmcnt(62)
; __device__ __forceinline__ float bf2f(unsigned h) { return __uint_as_float(h << 16); }
; __device__ __forceinline__ unsigned f2bf(float f) { unsigned u = __float_as_uint(f); return (u + 0x7fffu + ((u >> 16) & 1u)) >> 16; }
; __device__ __forceinline__ int crow(int r, int hi) { return (r & 3) + 8 * (r >> 2) + 4 * hi; }
; __device__ __forceinline__ void na_unit3(char* lds, const bf16_t* __restrict__ Qp, const bf16_t* __restrict__ Knp, const bf16_t* __restrict__ Vp, ...
;     ...
;     for (int r = 0; r < 16; ++r) { const long trow = wid * QBLK + crow(r, hi);
; #pragma unroll
;       for (int d0 = 0; d0 < 4; ++d0) { const float z = bf2f(zr[r][d0]); const float v = o[d0][r] * rli[r];
;         const float g = v * z * __builtin_amdgcn_rcpf(1.f + __expf(-z));
;         Op[((size_t)(d0 >> 1) * M_TOK + trow) * 64 + (d0 & 1) * 32 + r32] = (bf16_t)f2bf(g); } } }
	v_lshlrev_b32_e32 v18, 16, v147
	v_mul_f32_e32 v19, v38, v139
	v_mul_f32_e32 v19, v19, v18
	v_mul_f32_e32 v18, 0xbfb8aa3b, v18
	v_exp_f32_e32 v18, v18
	v_add_co_u32_e32 v16, vcc, s93, v16
	v_add_f32_e32 v18, 1.0, v18
	v_rcp_f32_e32 v18, v18
	v_addc_co_u32_e32 v17, vcc, 0, v17, vcc
	v_mul_f32_e32 v18, v19, v18
	v_bfe_u32 v19, v18, 16, 1
	v_add3_u32 v18, v18, v19, s63
	global_store_short_d16_hi v[16:17], v18, off
	v_lshlrev_b32_e32 v18, 16, v146
	v_mul_f32_e32 v19, v22, v139
	v_mul_f32_e32 v19, v19, v18
	v_mul_f32_e32 v18, 0xbfb8aa3b, v18
	v_exp_f32_e32 v18, v18
	s_nop 0
	v_add_f32_e32 v18, 1.0, v18
	v_rcp_f32_e32 v18, v18
	s_nop 0
	v_mul_f32_e32 v18, v19, v18
	v_bfe_u32 v19, v18, 16, 1
	v_add3_u32 v18, v18, v19, s63
	global_store_short_d16_hi v[16:17], v18, off offset:64
	s_waitcnt vmcnt(62)
	v_lshlrev_b32_e32 v16, 16, v145
	v_mul_f32_e32 v17, v71, v133
	v_mul_f32_e32 v17, v17, v16
	v_mul_f32_e32 v16, 0xbfb8aa3b, v16
	v_exp_f32_e32 v16, v16
	v_mul_f32_e32 v19, v55, v133
	v_add_f32_e32 v16, 1.0, v16
	v_rcp_f32_e32 v16, v16
	s_nop 0
	v_mul_f32_e32 v16, v17, v16
	v_bfe_u32 v17, v16, 16, 1
	v_add3_u32 v18, v16, v17, s63
	v_lshlrev_b64 v[16:17], 7, v[84:85]
	v_lshl_add_u64 v[16:17], s[34:35], 0, v[16:17]
	v_lshl_add_u64 v[16:17], v[16:17], 0, v[2:3]
	global_store_short_d16_hi v[16:17], v18, off
	v_lshlrev_b32_e32 v18, 16, v143
	v_mul_f32_e32 v19, v19, v18
	v_mul_f32_e32 v18, 0xbfb8aa3b, v18
	v_exp_f32_e32 v18, v18
	s_nop 0
	v_add_f32_e32 v18, 1.0, v18
	v_rcp_f32_e32 v18, v18
	s_nop 0
	v_mul_f32_e32 v18, v19, v18
	v_bfe_u32 v19, v18, 16, 1
	v_add3_u32 v18, v18, v19, s63
	global_store_short_d16_hi v[16:17], v18, off offset:64
	s_waitcnt vmcnt(62)
	v_lshlrev_b32_e32 v18, 16, v142
	v_mul_f32_e32 v19, v39, v133
	v_mul_f32_e32 v19, v19, v18
	v_mul_f32_e32 v18, 0xbfb8aa3b, v18
	v_exp_f32_e32 v18, v18
	v_add_co_u32_e32 v16, vcc, s93, v16
	v_add_f32_e32 v18, 1.0, v18
	v_rcp_f32_e32 v18, v18
	v_addc_co_u32_e32 v17, vcc, 0, v17, vcc
	v_mul_f32_e32 v18, v19, v18
	v_bfe_u32 v19, v18, 16, 1
	v_add3_u32 v18, v18, v19, s63
	global_store_short_d16_hi v[16:17], v18, off
	v_lshlrev_b32_e32 v18, 16, v141
	v_mul_f32_e32 v19, v23, v133
	v_mul_f32_e32 v19, v19, v18
	v_mul_f32_e32 v18, 0xbfb8aa3b, v18
	v_exp_f32_e32 v18, v18
	s_nop 0
	v_add_f32_e32 v18, 1.0, v18
	v_rcp_f32_e32 v18, v18
	s_nop 0
	v_mul_f32_e32 v18, v19, v18
	v_bfe_u32 v19, v18, 16, 1
	v_add3_u32 v18, v18, v19, s63
	global_store_short_d16_hi v[16:17], v18, off offset:64
	s_waitcnt vmcnt(62)
	v_lshlrev_b32_e32 v16, 16, v140
	v_mul_f32_e32 v17, v72, v128
	v_mul_f32_e32 v17, v17, v16
	v_mul_f32_e32 v16, 0xbfb8aa3b, v16
	v_exp_f32_e32 v16, v16
	v_mul_f32_e32 v19, v56, v128
	v_add_f32_e32 v16, 1.0, v16
	v_rcp_f32_e32 v16, v16
	s_nop 0
	v_mul_f32_e32 v16, v17, v16
	v_bfe_u32 v17, v16, 16, 1
	v_add3_u32 v18, v16, v17, s63
	v_lshlrev_b64 v[16:17], 7, v[82:83]
	v_lshl_add_u64 v[16:17], s[34:35], 0, v[16:17]
	v_lshl_add_u64 v[16:17], v[16:17], 0, v[2:3]
	global_store_short_d16_hi v[16:17], v18, off
	v_lshlrev_b32_e32 v18, 16, v138
	v_mul_f32_e32 v19, v19, v18
	v_mul_f32_e32 v18, 0xbfb8aa3b, v18
	v_exp_f32_e32 v18, v18
	s_nop 0
	v_add_f32_e32 v18, 1.0, v18
	v_rcp_f32_e32 v18, v18
	s_nop 0
	v_mul_f32_e32 v18, v19, v18
	v_bfe_u32 v19, v18, 16, 1
	v_add3_u32 v18, v18, v19, s63
	global_store_short_d16_hi v[16:17], v18, off offset:64
	s_waitcnt vmcnt(62)
	v_lshlrev_b32_e32 v18, 16, v137
	v_mul_f32_e32 v19, v40, v128
	v_mul_f32_e32 v19, v19, v18
	v_mul_f32_e32 v18, 0xbfb8aa3b, v18
	v_exp_f32_e32 v18, v18
	v_add_co_u32_e32 v16, vcc, s93, v16
	v_add_f32_e32 v18, 1.0, v18
	v_rcp_f32_e32 v18, v18
	v_addc_co_u32_e32 v17, vcc, 0, v17, vcc
	v_mul_f32_e32 v18, v19, v18
	v_bfe_u32 v19, v18, 16, 1
	v_add3_u32 v18, v18, v19, s63
	global_store_short_d16_hi v[16:17], v18, off
	v_lshlrev_b32_e32 v18, 16, v136
	v_mul_f32_e32 v19, v24, v128
	v_mul_f32_e32 v19, v19, v18
	v_mul_f32_e32 v18, 0xbfb8aa3b, v18
	v_exp_f32_e32 v18, v18
	s_nop 0
	v_add_f32_e32 v18, 1.0, v18
	v_rcp_f32_e32 v18, v18
	s_nop 0
	v_mul_f32_e32 v18, v19, v18
	v_bfe_u32 v19, v18, 16, 1
	v_add3_u32 v18, v18, v19, s63
	global_store_short_d16_hi v[16:17], v18, off offset:64
	s_waitcnt vmcnt(62)
	v_lshlrev_b32_e32 v16, 16, v135
	v_mul_f32_e32 v17, v73, v122
	v_mul_f32_e32 v17, v17, v16
	v_mul_f32_e32 v16, 0xbfb8aa3b, v16
	v_exp_f32_e32 v16, v16
	v_mul_f32_e32 v19, v57, v122
	v_add_f32_e32 v16, 1.0, v16
	v_rcp_f32_e32 v16, v16
	s_nop 0
	v_mul_f32_e32 v16, v17, v16
	v_bfe_u32 v17, v16, 16, 1
	v_add3_u32 v18, v16, v17, s63
	v_lshlrev_b64 v[16:17], 7, v[80:81]
	v_lshl_add_u64 v[16:17], s[34:35], 0, v[16:17]
	v_lshl_add_u64 v[16:17], v[16:17], 0, v[2:3]
	global_store_short_d16_hi v[16:17], v18, off
	v_lshlrev_b32_e32 v18, 16, v134
	v_mul_f32_e32 v19, v19, v18
	v_mul_f32_e32 v18, 0xbfb8aa3b, v18
	v_exp_f32_e32 v18, v18
	v_lshl_add_u64 v[2:3], v[4:5], 0, v[2:3]
	s_waitcnt vmcnt(39)
	v_lshlrev_b32_e32 v4, 16, v104
	v_mul_f32_e32 v5, v63, v1
	v_add_f32_e32 v18, 1.0, v18
	v_rcp_f32_e32 v18, v18
	v_mul_f32_e32 v5, v5, v4
	v_mul_f32_e32 v4, 0xbfb8aa3b, v4
	v_exp_f32_e32 v4, v4
	v_mul_f32_e32 v18, v19, v18
	v_bfe_u32 v19, v18, 16, 1
	v_add3_u32 v18, v18, v19, s63
	global_store_short_d16_hi v[16:17], v18, off offset:64
	v_lshlrev_b32_e32 v18, 16, v132
	v_mul_f32_e32 v19, v41, v122
	v_mul_f32_e32 v19, v19, v18
	v_mul_f32_e32 v18, 0xbfb8aa3b, v18
	v_exp_f32_e32 v18, v18
	v_add_co_u32_e32 v16, vcc, s93, v16
	v_add_f32_e32 v4, 1.0, v4
	v_add_f32_e32 v18, 1.0, v18
	v_rcp_f32_e32 v18, v18
	v_addc_co_u32_e32 v17, vcc, 0, v17, vcc
	v_rcp_f32_e32 v4, v4
	v_mul_f32_e32 v18, v19, v18
	v_bfe_u32 v19, v18, 16, 1
	v_add3_u32 v18, v18, v19, s63
	global_store_short_d16_hi v[16:17], v18, off
	v_lshlrev_b32_e32 v18, 16, v131
	v_mul_f32_e32 v19, v25, v122
	v_mul_f32_e32 v19, v19, v18
	v_mul_f32_e32 v18, 0xbfb8aa3b, v18
	v_exp_f32_e32 v18, v18
	v_mul_f32_e32 v4, v5, v4
	v_bfe_u32 v5, v4, 16, 1
	v_add3_u32 v4, v4, v5, s63
	v_add_f32_e32 v18, 1.0, v18
	v_rcp_f32_e32 v18, v18
	global_store_short_d16_hi v[2:3], v4, off offset:64
	s_waitcnt vmcnt(41)
; __device__ __forceinline__ float bf2f(unsigned h) { return __uint_as_float(h << 16); }
; __device__ __forceinline__ unsigned f2bf(float f) { unsigned u = __float_as_uint(f); return (u + 0x7fffu + ((u >> 16) & 1u)) >> 16; }
; __device__ __forceinline__ int crow(int r, int hi) { return (r & 3) + 8 * (r >> 2) + 4 * hi; }
; __device__ __forceinline__ void na_unit3(char* lds, const bf16_t* __restrict__ Qp, const bf16_t* __restrict__ Knp, const bf16_t* __restrict__ Vp, ...
;     ...
;     for (int r = 0; r < 16; ++r) { const long trow = wid * QBLK + crow(r, hi);
; #pragma unroll
;       for (int d0 = 0; d0 < 4; ++d0) { const float z = bf2f(zr[r][d0]); const float v = o[d0][r] * rli[r];
;         const float g = v * z * __builtin_amdgcn_rcpf(1.f + __expf(-z));
;         Op[((size_t)(d0 >> 1) * M_TOK + trow) * 64 + (d0 & 1) * 32 + r32] = (bf16_t)f2bf(g); } } }
	v_lshlrev_b32_e32 v4, 16, v101
	v_mul_f32_e32 v5, v47, v1
	v_mul_f32_e32 v18, v19, v18
	v_bfe_u32 v19, v18, 16, 1
	v_add3_u32 v18, v18, v19, s63
	global_store_short_d16_hi v[16:17], v18, off offset:64
	v_lshlrev_b32_e32 v16, 16, v130
	v_mul_f32_e32 v17, v74, v117
	v_mul_f32_e32 v17, v17, v16
	v_mul_f32_e32 v16, 0xbfb8aa3b, v16
	v_exp_f32_e32 v16, v16
	v_mul_f32_e32 v5, v5, v4
	v_mul_f32_e32 v4, 0xbfb8aa3b, v4
	v_exp_f32_e32 v4, v4
	v_add_f32_e32 v16, 1.0, v16
	v_rcp_f32_e32 v16, v16
	v_add_f32_e32 v4, 1.0, v4
	v_rcp_f32_e32 v4, v4
	v_mul_f32_e32 v16, v17, v16
	v_bfe_u32 v17, v16, 16, 1
	v_add3_u32 v16, v16, v17, s63
	global_store_short_d16_hi v[14:15], v16, off
	v_lshlrev_b32_e32 v16, 16, v129
	v_mul_f32_e32 v17, v58, v117
	v_mul_f32_e32 v17, v17, v16
	v_mul_f32_e32 v16, 0xbfb8aa3b, v16
	v_exp_f32_e32 v16, v16
	v_mul_f32_e32 v4, v5, v4
	v_bfe_u32 v5, v4, 16, 1
	v_add3_u32 v4, v4, v5, s63
	v_add_f32_e32 v16, 1.0, v16
	v_rcp_f32_e32 v16, v16
	s_nop 0
	v_mul_f32_e32 v16, v17, v16
	v_bfe_u32 v17, v16, 16, 1
	v_add3_u32 v16, v16, v17, s63
	global_store_short_d16_hi v[14:15], v16, off offset:64
	v_lshlrev_b32_e32 v16, 16, v127
	v_mul_f32_e32 v17, v42, v117
	v_mul_f32_e32 v17, v17, v16
	v_mul_f32_e32 v16, 0xbfb8aa3b, v16
	v_exp_f32_e32 v16, v16
	v_add_co_u32_e32 v14, vcc, s93, v14
	v_add_f32_e32 v16, 1.0, v16
	v_rcp_f32_e32 v16, v16
	v_addc_co_u32_e32 v15, vcc, 0, v15, vcc
	v_mul_f32_e32 v16, v17, v16
	v_bfe_u32 v17, v16, 16, 1
	v_add3_u32 v16, v16, v17, s63
	global_store_short_d16_hi v[14:15], v16, off
	v_lshlrev_b32_e32 v16, 16, v126
	v_mul_f32_e32 v17, v26, v117
	v_mul_f32_e32 v17, v17, v16
	v_mul_f32_e32 v16, 0xbfb8aa3b, v16
	v_exp_f32_e32 v16, v16
	s_nop 0
	v_add_f32_e32 v16, 1.0, v16
	v_rcp_f32_e32 v16, v16
	s_nop 0
	v_mul_f32_e32 v16, v17, v16
	v_bfe_u32 v17, v16, 16, 1
	v_add3_u32 v16, v16, v17, s63
	global_store_short_d16_hi v[14:15], v16, off offset:64
	v_lshlrev_b32_e32 v14, 16, v125
	v_mul_f32_e32 v15, v75, v111
	v_mul_f32_e32 v15, v15, v14
	v_mul_f32_e32 v14, 0xbfb8aa3b, v14
	v_exp_f32_e32 v14, v14
	s_nop 0
	v_add_f32_e32 v14, 1.0, v14
	v_rcp_f32_e32 v14, v14
	s_nop 0
	v_mul_f32_e32 v14, v15, v14
	v_bfe_u32 v15, v14, 16, 1
	v_add3_u32 v14, v14, v15, s63
	global_store_short_d16_hi v[12:13], v14, off
	v_lshlrev_b32_e32 v14, 16, v124
	v_mul_f32_e32 v15, v59, v111
	v_mul_f32_e32 v15, v15, v14
	v_mul_f32_e32 v14, 0xbfb8aa3b, v14
	v_exp_f32_e32 v14, v14
	s_nop 0
	v_add_f32_e32 v14, 1.0, v14
	v_rcp_f32_e32 v14, v14
	s_nop 0
	v_mul_f32_e32 v14, v15, v14
	v_bfe_u32 v15, v14, 16, 1
	v_add3_u32 v14, v14, v15, s63
	global_store_short_d16_hi v[12:13], v14, off offset:64
	v_lshlrev_b32_e32 v14, 16, v123
	v_mul_f32_e32 v15, v43, v111
	v_mul_f32_e32 v15, v15, v14
	v_mul_f32_e32 v14, 0xbfb8aa3b, v14
	v_exp_f32_e32 v14, v14
	v_add_co_u32_e32 v12, vcc, s93, v12
	v_add_f32_e32 v14, 1.0, v14
	v_rcp_f32_e32 v14, v14
	v_addc_co_u32_e32 v13, vcc, 0, v13, vcc
	v_mul_f32_e32 v14, v15, v14
	v_bfe_u32 v15, v14, 16, 1
	v_add3_u32 v14, v14, v15, s63
	global_store_short_d16_hi v[12:13], v14, off
	v_lshlrev_b32_e32 v14, 16, v121
	v_mul_f32_e32 v15, v27, v111
	v_mul_f32_e32 v15, v15, v14
	v_mul_f32_e32 v14, 0xbfb8aa3b, v14
	v_exp_f32_e32 v14, v14
	s_nop 0
	v_add_f32_e32 v14, 1.0, v14
	v_rcp_f32_e32 v14, v14
	s_nop 0
	v_mul_f32_e32 v14, v15, v14
	v_bfe_u32 v15, v14, 16, 1
	v_add3_u32 v14, v14, v15, s63
	global_store_short_d16_hi v[12:13], v14, off offset:64
	v_lshlrev_b32_e32 v12, 16, v120
	v_mul_f32_e32 v13, v76, v105
	v_mul_f32_e32 v13, v13, v12
	v_mul_f32_e32 v12, 0xbfb8aa3b, v12
	v_exp_f32_e32 v12, v12
	s_nop 0
	v_add_f32_e32 v12, 1.0, v12
	v_rcp_f32_e32 v12, v12
	s_nop 0
	v_mul_f32_e32 v12, v13, v12
	v_bfe_u32 v13, v12, 16, 1
	v_add3_u32 v12, v12, v13, s63
	global_store_short_d16_hi v[10:11], v12, off
	v_lshlrev_b32_e32 v12, 16, v119
	v_mul_f32_e32 v13, v60, v105
	v_mul_f32_e32 v13, v13, v12
	v_mul_f32_e32 v12, 0xbfb8aa3b, v12
	v_exp_f32_e32 v12, v12
	s_nop 0
	v_add_f32_e32 v12, 1.0, v12
	v_rcp_f32_e32 v12, v12
	s_nop 0
	v_mul_f32_e32 v12, v13, v12
	v_bfe_u32 v13, v12, 16, 1
	v_add3_u32 v12, v12, v13, s63
	global_store_short_d16_hi v[10:11], v12, off offset:64
	v_lshlrev_b32_e32 v12, 16, v118
	v_mul_f32_e32 v13, v44, v105
	v_mul_f32_e32 v13, v13, v12
	v_mul_f32_e32 v12, 0xbfb8aa3b, v12
	v_exp_f32_e32 v12, v12
	v_add_co_u32_e32 v10, vcc, s93, v10
	v_add_f32_e32 v12, 1.0, v12
	v_rcp_f32_e32 v12, v12
	v_addc_co_u32_e32 v11, vcc, 0, v11, vcc
; __device__ __forceinline__ int opaque_tid() { int t = threadIdx.x; asm volatile("" : "+v"(t)); return t; }
; __device__ __forceinline__ float bf2f(unsigned h) { return __uint_as_float(h << 16); }
; __device__ __forceinline__ unsigned f2bf(float f) { unsigned u = __float_as_uint(f); return (u + 0x7fffu + ((u >> 16) & 1u)) >> 16; }
; __device__ __forceinline__ int crow(int r, int hi) { return (r & 3) + 8 * (r >> 2) + 4 * hi; }
; __device__ __forceinline__ void na_unit3(char* lds, const bf16_t* __restrict__ Qp, const bf16_t* __restrict__ Knp, const bf16_t* __restrict__ Vp, ...
;     ...
;   const int tid = opaque_tid(), wid = __builtin_amdgcn_readfirstlane(tid >> 6), lane = tid & 63, r32 = lane & 31, hi = lane >> 5;
;     ...
;     for (int r = 0; r < 16; ++r) { const long trow = wid * QBLK + crow(r, hi);
; #pragma unroll
;       for (int d0 = 0; d0 < 4; ++d0) { const float z = bf2f(zr[r][d0]); const float v = o[d0][r] * rli[r];
;         const float g = v * z * __builtin_amdgcn_rcpf(1.f + __expf(-z));
;         Op[((size_t)(d0 >> 1) * M_TOK + trow) * 64 + (d0 & 1) * 32 + r32] = (bf16_t)f2bf(g); } } }
;   asm volatile("s_waitcnt vmcnt(0) lgkmcnt(0)\n\ts_barrier" ::: "memory");
	v_mul_f32_e32 v12, v13, v12
	v_bfe_u32 v13, v12, 16, 1
	v_add3_u32 v12, v12, v13, s63
	global_store_short_d16_hi v[10:11], v12, off
	v_lshlrev_b32_e32 v12, 16, v116
	v_mul_f32_e32 v13, v28, v105
	v_mul_f32_e32 v13, v13, v12
	v_mul_f32_e32 v12, 0xbfb8aa3b, v12
	v_exp_f32_e32 v12, v12
	s_nop 0
	v_add_f32_e32 v12, 1.0, v12
	v_rcp_f32_e32 v12, v12
	s_nop 0
	v_mul_f32_e32 v12, v13, v12
	v_bfe_u32 v13, v12, 16, 1
	v_add3_u32 v12, v12, v13, s63
	global_store_short_d16_hi v[10:11], v12, off offset:64
	v_lshlrev_b32_e32 v10, 16, v115
	v_mul_f32_e32 v11, v77, v103
	v_mul_f32_e32 v11, v11, v10
	v_mul_f32_e32 v10, 0xbfb8aa3b, v10
	v_exp_f32_e32 v10, v10
	s_nop 0
	v_add_f32_e32 v10, 1.0, v10
	v_rcp_f32_e32 v10, v10
	s_nop 0
	v_mul_f32_e32 v10, v11, v10
	v_bfe_u32 v11, v10, 16, 1
	v_add3_u32 v10, v10, v11, s63
	global_store_short_d16_hi v[8:9], v10, off
	v_lshlrev_b32_e32 v10, 16, v114
	v_mul_f32_e32 v11, v61, v103
	v_mul_f32_e32 v11, v11, v10
	v_mul_f32_e32 v10, 0xbfb8aa3b, v10
	v_exp_f32_e32 v10, v10
	s_nop 0
	v_add_f32_e32 v10, 1.0, v10
	v_rcp_f32_e32 v10, v10
	s_nop 0
	v_mul_f32_e32 v10, v11, v10
	v_bfe_u32 v11, v10, 16, 1
	v_add3_u32 v10, v10, v11, s63
	global_store_short_d16_hi v[8:9], v10, off offset:64
	v_lshlrev_b32_e32 v10, 16, v113
	v_mul_f32_e32 v11, v45, v103
	v_mul_f32_e32 v11, v11, v10
	v_mul_f32_e32 v10, 0xbfb8aa3b, v10
	v_exp_f32_e32 v10, v10
	v_add_co_u32_e32 v8, vcc, s93, v8
	v_add_f32_e32 v10, 1.0, v10
	v_rcp_f32_e32 v10, v10
	v_addc_co_u32_e32 v9, vcc, 0, v9, vcc
	v_mul_f32_e32 v10, v11, v10
	v_bfe_u32 v11, v10, 16, 1
	v_add3_u32 v10, v10, v11, s63
	global_store_short_d16_hi v[8:9], v10, off
	v_lshlrev_b32_e32 v10, 16, v112
	v_mul_f32_e32 v11, v29, v103
	v_mul_f32_e32 v11, v11, v10
	v_mul_f32_e32 v10, 0xbfb8aa3b, v10
	v_exp_f32_e32 v10, v10
	s_nop 0
	v_add_f32_e32 v10, 1.0, v10
	v_rcp_f32_e32 v10, v10
	s_nop 0
	v_mul_f32_e32 v10, v11, v10
	v_bfe_u32 v11, v10, 16, 1
	v_add3_u32 v10, v10, v11, s63
	global_store_short_d16_hi v[8:9], v10, off offset:64
	v_lshlrev_b32_e32 v8, 16, v110
	v_mul_f32_e32 v9, v78, v102
	v_mul_f32_e32 v9, v9, v8
	v_mul_f32_e32 v8, 0xbfb8aa3b, v8
	v_exp_f32_e32 v8, v8
	s_nop 0
	v_add_f32_e32 v8, 1.0, v8
	v_rcp_f32_e32 v8, v8
	s_nop 0
	v_mul_f32_e32 v8, v9, v8
	v_bfe_u32 v9, v8, 16, 1
	v_add3_u32 v8, v8, v9, s63
	global_store_short_d16_hi v[6:7], v8, off
	v_lshlrev_b32_e32 v8, 16, v109
	v_mul_f32_e32 v9, v62, v102
	v_mul_f32_e32 v9, v9, v8
	v_mul_f32_e32 v8, 0xbfb8aa3b, v8
	v_exp_f32_e32 v8, v8
	s_nop 0
	v_add_f32_e32 v8, 1.0, v8
	v_rcp_f32_e32 v8, v8
	s_nop 0
	v_mul_f32_e32 v8, v9, v8
	v_bfe_u32 v9, v8, 16, 1
	v_add3_u32 v8, v8, v9, s63
	global_store_short_d16_hi v[6:7], v8, off offset:64
	v_lshlrev_b32_e32 v8, 16, v108
	v_mul_f32_e32 v9, v46, v102
	v_mul_f32_e32 v9, v9, v8
	v_mul_f32_e32 v8, 0xbfb8aa3b, v8
	v_exp_f32_e32 v8, v8
	v_add_co_u32_e32 v6, vcc, s93, v6
	v_add_f32_e32 v8, 1.0, v8
	v_rcp_f32_e32 v8, v8
	v_addc_co_u32_e32 v7, vcc, 0, v7, vcc
	v_mul_f32_e32 v8, v9, v8
	v_bfe_u32 v9, v8, 16, 1
	v_add3_u32 v8, v8, v9, s63
	global_store_short_d16_hi v[6:7], v8, off
	v_lshlrev_b32_e32 v8, 16, v107
	v_mul_f32_e32 v9, v30, v102
	v_mul_f32_e32 v9, v9, v8
	v_mul_f32_e32 v8, 0xbfb8aa3b, v8
	v_exp_f32_e32 v8, v8
	s_nop 0
	v_add_f32_e32 v8, 1.0, v8
	v_rcp_f32_e32 v8, v8
	s_nop 0
	v_mul_f32_e32 v8, v9, v8
	v_bfe_u32 v9, v8, 16, 1
	v_add3_u32 v8, v8, v9, s63
	global_store_short_d16_hi v[6:7], v8, off offset:64
	v_lshlrev_b32_e32 v6, 16, v106
	v_mul_f32_e32 v7, v79, v1
	v_mul_f32_e32 v7, v7, v6
	v_mul_f32_e32 v6, 0xbfb8aa3b, v6
	v_exp_f32_e32 v6, v6
	v_mul_f32_e32 v1, v31, v1
	v_add_f32_e32 v6, 1.0, v6
	v_rcp_f32_e32 v6, v6
	s_nop 0
	v_mul_f32_e32 v6, v7, v6
	v_bfe_u32 v7, v6, 16, 1
	v_add3_u32 v6, v6, v7, s63
	global_store_short_d16_hi v[2:3], v6, off
	v_add_co_u32_e32 v2, vcc, s93, v2
	s_nop 1
	v_addc_co_u32_e32 v3, vcc, 0, v3, vcc
	global_store_short_d16_hi v[2:3], v4, off
	s_waitcnt vmcnt(62)
	v_lshlrev_b32_e32 v4, 16, v100
	v_mul_f32_e32 v1, v1, v4
	v_mul_f32_e32 v4, 0xbfb8aa3b, v4
	v_exp_f32_e32 v4, v4
	s_nop 0
	v_add_f32_e32 v4, 1.0, v4
	v_rcp_f32_e32 v4, v4
	s_nop 0
	v_mul_f32_e32 v1, v1, v4
	v_bfe_u32 v4, v1, 16, 1
	v_add3_u32 v1, v1, v4, s63
	global_store_short_d16_hi v[2:3], v1, off offset:64
	s_setprio 0
	s_waitcnt vmcnt(0) lgkmcnt(0)
	s_barrier
	s_cbranch_scc1 .LBB0_352
.LBB0_276:
	v_readfirstlane_b32 s100, v252
	s_lshr_b32 s100, s100, 8
	s_cmp_eq_u32 s100, 0
	s_cbranch_scc1 .Lna_prio_skip
	s_setprio 1
